# context-hyena items: remaining pass-A weight/tap loads (6 serialized round trips) hoisted into two groups, pass-C second-chunk loads issued with the first chunk
# speedup vs baseline: 1.0040x; 1.0040x over previous
.LBB0_719:
	s_or_b64 exec, exec, s[36:37]
	s_add_i32 s20, s19, 0xfffffe00
	v_ashrrev_i32_e32 v11, 31, v10
	s_lshr_b32 s23, s20, 5
	v_add_u32_e32 v18, -1, v0
	s_lshl_b32 s21, s23, 8
	v_lshl_add_u64 v[10:11], v[10:11], 2, s[26:27]
	v_med3_i32 v19, v18, 0, v201
	global_load_dword v110, v[10:11], off
	v_or_b32_e32 v10, s21, v19
	v_mul_lo_u32 v160, v10, s0
	v_lshl_add_u64 v[104:105], s[6:7], 0, v[160:161]
	s_mov_b64 s[40:41], 0x2400
	v_lshl_add_u64 v[118:119], v[104:105], 0, s[40:41]
	s_lshl_b32 s70, s46, 1
	v_lshl_add_u64 v[10:11], v[118:119], 0, s[70:71]
	global_load_dwordx4 v[10:13], v[10:11], off
	s_mov_b64 s[48:49], 0x2c00
	v_lshl_add_u64 v[116:117], v[104:105], 0, s[48:49]
	v_lshl_add_u64 v[14:15], v[116:117], 0, s[70:71]
	global_load_dwordx4 v[14:17], v[14:15], off
	v_cmp_eq_u32_e64 s[36:37], v18, v19
	v_med3_i32 v18, v0, 0, v201
	v_cmp_eq_u32_e64 s[38:39], v0, v18
	s_or_b32 s20, s46, 8
	s_lshl_b32 s50, s46, 2
	v_mov_b32_e32 v34, s50
	v_lshlrev_b32_e32 v131, 3, v125
	v_lshrrev_b32_e32 v130, 4, v125
	v_and_b32_e32 v129, 15, v0
	s_mov_b32 s52, 0
	v_or_b32_e32 v204, s21, v18
	v_mul_lo_u32 v160, v204, s0
	v_lshl_add_u64 v[106:107], s[6:7], 0, v[160:161]
	v_lshl_add_u64 v[122:123], v[106:107], 0, s[40:41]
	v_lshl_add_u64 v[206:207], v[122:123], 0, s[70:71]
	global_load_dwordx4 v[208:211], v[206:207], off
	v_lshl_add_u64 v[112:113], v[106:107], 0, s[48:49]
	v_lshl_add_u64 v[212:213], v[112:113], 0, s[70:71]
	global_load_dwordx4 v[214:217], v[212:213], off
	v_add_u32_e32 v18, 1, v0
	v_med3_i32 v19, v18, 0, v201
	v_or_b32_e32 v205, s21, v19
	v_mul_lo_u32 v160, v205, s0
	v_lshl_add_u64 v[108:109], s[6:7], 0, v[160:161]
	v_lshl_add_u64 v[120:121], v[108:109], 0, s[40:41]
	v_lshl_add_u64 v[218:219], v[120:121], 0, s[70:71]
	global_load_dwordx4 v[220:223], v[218:219], off
	v_lshl_add_u64 v[114:115], v[108:109], 0, s[48:49]
	v_lshl_add_u64 v[224:225], v[114:115], 0, s[70:71]
	global_load_dwordx4 v[226:229], v[224:225], off
	s_add_u32 s48, s82, s50
	s_addc_u32 s49, s83, 0
	s_add_u32 s46, s48, 0x1000
	s_addc_u32 s47, s49, 0
	global_load_dwordx4 v[230:233], v161, s[46:47] offset:48
	global_load_dwordx4 v[234:237], v161, s[46:47] offset:32
	global_load_dwordx4 v[72:75], v161, s[46:47] offset:16
	global_load_dwordx4 v[80:83], v195, s[48:49]
	global_load_dwordx4 v[238:241], v34, s[82:83] offset:48
	global_load_dwordx4 v[22:25], v34, s[82:83] offset:32
	global_load_dwordx4 v[76:79], v34, s[82:83] offset:16
	global_load_dwordx4 v[84:87], v34, s[82:83]
	global_load_dwordx4 v[26:29], v34, s[80:81] offset:48
	global_load_dwordx4 v[30:33], v34, s[80:81] offset:32
	global_load_dwordx4 v[42:45], v34, s[80:81] offset:16
	global_load_dwordx4 v[46:49], v34, s[80:81]
	s_add_u32 s46, s80, s50
	s_addc_u32 s47, s81, 0
	s_add_u32 s50, s46, 0x1000
	s_addc_u32 s51, s47, 0
	global_load_dwordx4 v[242:245], v161, s[50:51] offset:48
	global_load_dwordx4 v[38:41], v161, s[50:51] offset:32
	global_load_dwordx4 v[50:53], v161, s[50:51] offset:16
	global_load_dwordx4 v[54:57], v195, s[46:47]
	s_add_u32 s50, s46, 0x1800
	s_addc_u32 s51, s47, 0
	global_load_dwordx4 v[144:147], v161, s[50:51] offset:48
	global_load_dwordx4 v[152:155], v161, s[50:51] offset:32
	global_load_dwordx4 v[156:159], v161, s[50:51] offset:16
	global_load_dwordx4 v[92:95], v196, s[46:47] offset:2048
	global_load_dwordx4 v[96:99], v197, s[46:47]
	global_load_dwordx4 v[100:103], v198, s[46:47]
	s_waitcnt vmcnt(29)
	global_load_dwordx4 v[172:175], v195, s[46:47] offset:2048
	s_add_u32 s50, s46, 0x2800
	s_addc_u32 s51, s47, 0
	global_load_dwordx4 v[176:179], v161, s[50:51] offset:48
	global_load_dwordx4 v[180:183], v161, s[50:51] offset:32
	global_load_dwordx4 v[184:187], v161, s[50:51] offset:16
	s_waitcnt vmcnt(31)
	v_cndmask_b32_e64 v61, 0, v10, s[36:37]
	s_nop 0
	s_nop 0
	s_nop 0
	s_nop 0
	v_cndmask_b32_e64 v60, 0, v11, s[36:37]
	s_nop 0
	v_cndmask_b32_e64 v58, 0, v13, s[36:37]
	v_cndmask_b32_e64 v59, 0, v12, s[36:37]
	s_nop 0
	s_nop 0
	s_waitcnt vmcnt(30)
	v_cndmask_b32_e64 v88, 0, v15, s[36:37]
	v_cndmask_b32_e64 v89, 0, v14, s[36:37]
	s_nop 0
	v_cndmask_b32_e64 v70, 0, v17, s[36:37]
	v_cndmask_b32_e64 v71, 0, v16, s[36:37]
	s_nop 0
	s_nop 0
	s_nop 0
	v_lshlrev_b32_e32 v35, 16, v61
	s_waitcnt vmcnt(29)
	v_cndmask_b32_e64 v68, 0, v208, s[38:39]
	s_nop 0
	s_nop 0
	s_nop 0
	s_nop 0
	s_nop 0
	v_cndmask_b32_e64 v66, 0, v209, s[38:39]
	s_waitcnt vmcnt(28)
	v_cndmask_b32_e64 v67, 0, v215, s[38:39]
	v_cndmask_b32_e64 v69, 0, v214, s[38:39]
	s_nop 0
	s_nop 0
	v_cndmask_b32_e64 v62, 0, v211, s[38:39]
	v_cndmask_b32_e64 v64, 0, v210, s[38:39]
	v_cndmask_b32_e64 v63, 0, v217, s[38:39]
	v_cndmask_b32_e64 v65, 0, v216, s[38:39]
	s_nop 0
	s_nop 0
	s_nop 0
	s_nop 0
	s_nop 0
	v_cmp_eq_u32_e64 s[40:41], v18, v19
	s_nop 0
	v_lshlrev_b32_e32 v160, 1, v131
	s_waitcnt vmcnt(27)
	v_cndmask_b32_e64 v132, 0, v223, s[40:41]
	v_cndmask_b32_e64 v134, 0, v222, s[40:41]
	v_cndmask_b32_e64 v136, 0, v221, s[40:41]
	v_cndmask_b32_e64 v138, 0, v220, s[40:41]
	s_waitcnt vmcnt(26)
	s_waitcnt vmcnt(26)
	s_add_u32 s50, s46, 0x3000
	s_addc_u32 s51, s47, 0
	global_load_dwordx4 v[10:13], v161, s[50:51] offset:48
	global_load_dwordx4 v[14:17], v161, s[50:51] offset:32
	global_load_dwordx4 v[18:21], v161, s[50:51] offset:16
	s_add_u32 s50, s46, 0x4000
	s_addc_u32 s51, s47, 0
	global_load_dwordx4 v[204:207], v161, s[50:51] offset:48
	global_load_dwordx4 v[208:211], v161, s[50:51] offset:32
	global_load_dwordx4 v[212:215], v161, s[50:51] offset:16
	v_cndmask_b32_e64 v133, 0, v229, s[40:41]
	v_cndmask_b32_e64 v135, 0, v228, s[40:41]
	v_cndmask_b32_e64 v137, 0, v227, s[40:41]
	v_cndmask_b32_e64 v139, 0, v226, s[40:41]
	s_nop 0
	s_nop 0
	s_nop 0
	s_nop 0
	s_nop 0
	s_nop 0
	s_nop 0
	s_nop 0
	s_nop 0
	s_nop 0
	s_nop 0
	s_nop 0
	s_nop 0
	s_nop 0
	s_nop 0
	s_nop 0
	s_waitcnt vmcnt(20)
	v_fma_f32 v84, v46, v35, v84
	s_nop 0
	s_nop 0
	s_nop 0
	s_nop 0
	v_lshlrev_b32_e32 v46, 16, v89
	s_nop 0
	s_nop 0
	s_waitcnt vmcnt(16)
	v_fma_f32 v143, v54, v46, v80
	v_and_b32_e32 v46, 0xffff0000, v61
	v_fma_f32 v140, v47, v46, v85
	v_and_b32_e32 v46, 0xffff0000, v89
	v_fma_f32 v142, v55, v46, v81
	v_lshlrev_b32_e32 v46, 16, v60
	v_fma_f32 v85, v48, v46, v86
	v_lshlrev_b32_e32 v46, 16, v88
	v_fma_f32 v141, v56, v46, v82
	v_and_b32_e32 v46, 0xffff0000, v60
	v_fmac_f32_e32 v87, v49, v46
	v_and_b32_e32 v46, 0xffff0000, v88
	v_fmac_f32_e32 v83, v57, v46
	v_lshlrev_b32_e32 v46, 16, v59
	v_fma_f32 v80, v42, v46, v76
	v_lshlrev_b32_e32 v42, 16, v71
	v_fma_f32 v86, v50, v42, v72
	v_and_b32_e32 v42, 0xffff0000, v59
	v_fma_f32 v77, v43, v42, v77
	v_and_b32_e32 v42, 0xffff0000, v71
	v_fma_f32 v81, v51, v42, v73
	v_lshlrev_b32_e32 v42, 16, v58
	v_fma_f32 v76, v44, v42, v78
	v_lshlrev_b32_e32 v42, 16, v70
	v_fma_f32 v74, v52, v42, v74
	v_and_b32_e32 v42, 0xffff0000, v58
	v_fmac_f32_e32 v79, v45, v42
	v_and_b32_e32 v42, 0xffff0000, v70
	v_fmac_f32_e32 v75, v53, v42
	s_nop 0
	s_nop 0
	s_nop 0
	s_nop 0
	s_nop 0
	v_lshlrev_b32_e32 v50, 16, v68
	s_nop 0
	v_and_b32_e32 v68, 0xffff0000, v68
	v_lshlrev_b32_e32 v78, 16, v139
	v_lshl_add_u32 v82, v0, 1, s17
	s_waitcnt vmcnt(9)
	v_fmac_f32_e32 v84, v172, v50
	s_nop 0
	s_nop 0
	s_nop 0
	s_nop 0
	s_waitcnt vmcnt(8)
	v_mov_b32_e32 v50, v176
	v_mov_b32_e32 v51, v177
	v_mov_b32_e32 v52, v178
	v_mov_b32_e32 v53, v179
	s_waitcnt vmcnt(7)
	v_mov_b32_e32 v58, v180
	v_mov_b32_e32 v59, v181
	v_mov_b32_e32 v60, v182
	v_mov_b32_e32 v61, v183
	v_mov_b32_e32 v70, v172
	v_mov_b32_e32 v71, v173
	v_mov_b32_e32 v72, v174
	v_mov_b32_e32 v73, v175
	s_waitcnt vmcnt(6)
	v_mov_b32_e32 v88, v184
	v_mov_b32_e32 v89, v185
	v_mov_b32_e32 v90, v186
	v_mov_b32_e32 v91, v187
	v_fmac_f32_e32 v140, v71, v68
	v_and_b32_e32 v68, 0xffff0000, v69
	s_nop 0
	s_nop 0
	v_lshlrev_b32_e32 v70, 16, v69
	v_fmac_f32_e32 v142, v93, v68
	v_lshlrev_b32_e32 v68, 16, v66
	v_and_b32_e32 v66, 0xffff0000, v66
	v_fmac_f32_e32 v87, v73, v66
	v_and_b32_e32 v66, 0xffff0000, v67
	v_fmac_f32_e32 v83, v95, v66
	v_lshlrev_b32_e32 v66, 16, v64
	v_fmac_f32_e32 v80, v156, v66
	v_lshlrev_b32_e32 v54, 16, v65
	v_fmac_f32_e32 v86, v88, v54
	v_and_b32_e32 v54, 0xffff0000, v64
	v_fmac_f32_e32 v77, v157, v54
	v_and_b32_e32 v54, 0xffff0000, v65
	v_fmac_f32_e32 v81, v89, v54
	v_lshlrev_b32_e32 v54, 16, v62
	v_fmac_f32_e32 v76, v158, v54
	v_lshlrev_b32_e32 v54, 16, v63
	v_fmac_f32_e32 v74, v90, v54
	v_and_b32_e32 v54, 0xffff0000, v62
	v_fmac_f32_e32 v79, v159, v54
	v_and_b32_e32 v54, 0xffff0000, v63
	v_fmac_f32_e32 v75, v91, v54
	s_nop 0
	s_nop 0
	s_nop 0
	s_nop 0
	s_nop 0
	v_fmac_f32_e32 v85, v72, v68
	v_lshlrev_b32_e32 v68, 16, v67
	v_lshlrev_b32_e32 v66, 16, v138
	s_nop 0
	v_fmac_f32_e32 v143, v92, v70
	v_fmac_f32_e32 v141, v94, v68
	v_fmac_f32_e32 v84, v96, v66
	s_nop 0
	s_nop 0
	s_nop 0
	s_nop 0
	s_waitcnt vmcnt(5)
	v_mov_b32_e32 v54, v10
	v_mov_b32_e32 v55, v11
	v_mov_b32_e32 v56, v12
	v_mov_b32_e32 v57, v13
	s_waitcnt vmcnt(4)
	v_mov_b32_e32 v62, v14
	v_mov_b32_e32 v63, v15
	v_mov_b32_e32 v64, v16
	v_mov_b32_e32 v65, v17
	s_waitcnt vmcnt(2)
	v_mov_b32_e32 v66, v204
	v_mov_b32_e32 v67, v205
	v_mov_b32_e32 v68, v206
	v_mov_b32_e32 v69, v207
	s_waitcnt vmcnt(1)
	v_mov_b32_e32 v70, v208
	v_mov_b32_e32 v71, v209
	v_mov_b32_e32 v72, v210
	v_mov_b32_e32 v73, v211
	v_mov_b32_e32 v88, v18
	v_mov_b32_e32 v89, v19
	v_mov_b32_e32 v90, v20
	v_mov_b32_e32 v91, v21
	s_waitcnt vmcnt(0)
	v_mov_b32_e32 v92, v212
	v_mov_b32_e32 v93, v213
	v_mov_b32_e32 v94, v214
	v_mov_b32_e32 v95, v215
	s_lshl_b32 s50, s20, 1
	s_mov_b32 s51, s71
	v_fmac_f32_e32 v143, v100, v78
	v_and_b32_e32 v78, 0xffff0000, v138
	v_fmac_f32_e32 v140, v97, v78
	v_and_b32_e32 v78, 0xffff0000, v139
	v_fmac_f32_e32 v142, v101, v78
	v_lshlrev_b32_e32 v78, 16, v136
	v_fmac_f32_e32 v85, v98, v78
	v_lshlrev_b32_e32 v78, 16, v137
	v_fmac_f32_e32 v141, v102, v78
	v_and_b32_e32 v78, 0xffff0000, v136
	v_fmac_f32_e32 v87, v99, v78
	v_and_b32_e32 v78, 0xffff0000, v137
	v_fmac_f32_e32 v83, v103, v78
	v_lshlrev_b32_e32 v78, 16, v134
	s_waitcnt vmcnt(3)
	v_fmac_f32_e32 v80, v88, v78
	v_lshlrev_b32_e32 v78, 16, v135
	s_waitcnt vmcnt(0)
	v_fmac_f32_e32 v86, v92, v78
	v_and_b32_e32 v78, 0xffff0000, v134
	v_fmac_f32_e32 v77, v89, v78
	v_and_b32_e32 v78, 0xffff0000, v135
	v_fmac_f32_e32 v81, v93, v78
	v_lshlrev_b32_e32 v78, 16, v132
	v_fmac_f32_e32 v76, v90, v78
	v_lshlrev_b32_e32 v78, 16, v133
	v_fmac_f32_e32 v74, v94, v78
	v_and_b32_e32 v78, 0xffff0000, v132
	v_fmac_f32_e32 v79, v91, v78
	v_and_b32_e32 v78, 0xffff0000, v133
	v_fmac_f32_e32 v75, v95, v78
	v_bfe_u32 v78, v143, 16, 1
	v_add3_u32 v78, v143, v78, s94
	ds_write_b16_d16_hi v82, v78 offset:512
	v_bfe_u32 v78, v84, 16, 1
	v_add3_u32 v78, v84, v78, s94
	ds_write_b16_d16_hi v82, v78 offset:24576
	v_bfe_u32 v78, v142, 16, 1
	v_add3_u32 v78, v142, v78, s94
	ds_write_b16_d16_hi v82, v78 offset:2048
	v_bfe_u32 v78, v140, 16, 1
	v_add3_u32 v78, v140, v78, s94
	ds_write_b16_d16_hi v82, v78 offset:25088
	v_bfe_u32 v78, v141, 16, 1
	v_add3_u32 v78, v141, v78, s94
	ds_write_b16_d16_hi v82, v78 offset:3584
	v_bfe_u32 v78, v85, 16, 1
	v_add3_u32 v78, v85, v78, s94
	ds_write_b16_d16_hi v82, v78 offset:25600
	v_bfe_u32 v78, v83, 16, 1
	v_add3_u32 v78, v83, v78, s94
	ds_write_b16_d16_hi v82, v78 offset:5120
	v_bfe_u32 v78, v87, 16, 1
	v_add3_u32 v78, v87, v78, s94
	ds_write_b16_d16_hi v82, v78 offset:26112
	v_bfe_u32 v78, v86, 16, 1
	v_add3_u32 v78, v86, v78, s94
	ds_write_b16_d16_hi v82, v78 offset:6656
	v_bfe_u32 v78, v80, 16, 1
	v_add3_u32 v78, v80, v78, s94
	ds_write_b16_d16_hi v82, v78 offset:26624
	v_bfe_u32 v78, v81, 16, 1
	s_waitcnt vmcnt(0)
	v_lshl_add_u64 v[132:133], v[118:119], 0, s[50:51]
	global_load_dwordx4 v[134:137], v[132:133], off
	v_lshl_add_u64 v[138:139], v[116:117], 0, s[50:51]
	global_load_dwordx4 v[140:143], v[138:139], off
	v_lshl_add_u64 v[156:157], v[122:123], 0, s[50:51]
	global_load_dwordx4 v[172:175], v[156:157], off
	v_lshl_add_u64 v[158:159], v[112:113], 0, s[50:51]
	global_load_dwordx4 v[176:179], v[158:159], off
	v_lshl_add_u64 v[180:181], v[120:121], 0, s[50:51]
	global_load_dwordx4 v[182:185], v[180:181], off
	v_lshl_add_u64 v[186:187], v[114:115], 0, s[50:51]
	global_load_dwordx4 v[204:207], v[186:187], off
	v_add3_u32 v78, v81, v78, s94
	ds_write_b16_d16_hi v82, v78 offset:8192
	v_bfe_u32 v78, v77, 16, 1
	v_add3_u32 v77, v77, v78, s94
	ds_write_b16_d16_hi v82, v77 offset:27136
	v_bfe_u32 v77, v74, 16, 1
	v_add3_u32 v74, v74, v77, s94
	ds_write_b16_d16_hi v82, v74 offset:9728
	v_bfe_u32 v74, v76, 16, 1
	v_add3_u32 v74, v76, v74, s94
	ds_write_b16_d16_hi v82, v74 offset:27648
	v_bfe_u32 v74, v75, 16, 1
	v_add3_u32 v74, v75, v74, s94
	ds_write_b16_d16_hi v82, v74 offset:11264
	v_bfe_u32 v74, v79, 16, 1
	v_add3_u32 v74, v79, v74, s94
	ds_write_b16_d16_hi v82, v74 offset:28160
	s_nop 0
	s_nop 0
	s_nop 0
	s_nop 0
	s_waitcnt vmcnt(5)
	v_cndmask_b32_e64 v85, 0, v135, s[36:37]
	v_cndmask_b32_e64 v86, 0, v134, s[36:37]
	s_nop 0
	v_cndmask_b32_e64 v83, 0, v137, s[36:37]
	v_cndmask_b32_e64 v84, 0, v136, s[36:37]
	s_waitcnt vmcnt(4)
	v_cndmask_b32_e64 v89, 0, v141, s[36:37]
	v_cndmask_b32_e64 v90, 0, v140, s[36:37]
	s_nop 0
	s_nop 0
	v_cndmask_b32_e64 v87, 0, v143, s[36:37]
	v_cndmask_b32_e64 v88, 0, v142, s[36:37]
	s_nop 0
	v_lshlrev_b32_e32 v99, 16, v86
	v_fma_f32 v22, v30, v99, v22
	v_lshlrev_b32_e32 v30, 16, v90
	v_fma_f32 v18, v38, v30, v234
	v_and_b32_e32 v30, 0xffff0000, v86
	v_fma_f32 v23, v31, v30, v23
	v_and_b32_e32 v30, 0xffff0000, v90
	v_fma_f32 v19, v39, v30, v235
	v_lshlrev_b32_e32 v30, 16, v85
	v_fma_f32 v24, v32, v30, v24
	v_lshlrev_b32_e32 v30, 16, v89
	v_fma_f32 v20, v40, v30, v236
	v_and_b32_e32 v30, 0xffff0000, v85
	v_fmac_f32_e32 v25, v33, v30
	v_and_b32_e32 v30, 0xffff0000, v89
	v_fmac_f32_e32 v237, v41, v30
	v_lshlrev_b32_e32 v30, 16, v84
	v_fma_f32 v14, v26, v30, v238
	v_lshlrev_b32_e32 v26, 16, v88
	v_fma_f32 v10, v242, v26, v230
	v_and_b32_e32 v26, 0xffff0000, v84
	v_fma_f32 v15, v27, v26, v239
	v_and_b32_e32 v26, 0xffff0000, v88
	v_fma_f32 v11, v243, v26, v231
	v_lshlrev_b32_e32 v26, 16, v83
	v_fma_f32 v16, v28, v26, v240
	v_lshlrev_b32_e32 v26, 16, v87
	v_fma_f32 v12, v244, v26, v232
	v_and_b32_e32 v26, 0xffff0000, v83
	v_fmac_f32_e32 v241, v29, v26
	v_and_b32_e32 v26, 0xffff0000, v87
	v_fmac_f32_e32 v233, v245, v26
	v_or_b32_e32 v39, v128, v127
	v_or_b32_e32 v40, 0x8000, v39
	s_waitcnt vmcnt(3)
	v_cndmask_b32_e64 v93, 0, v173, s[38:39]
	v_cndmask_b32_e64 v94, 0, v172, s[38:39]
	s_nop 0
	v_cndmask_b32_e64 v91, 0, v175, s[38:39]
	v_cndmask_b32_e64 v92, 0, v174, s[38:39]
	s_waitcnt vmcnt(2)
	v_cndmask_b32_e64 v97, 0, v177, s[38:39]
	v_cndmask_b32_e64 v98, 0, v176, s[38:39]
	s_nop 0
	s_nop 0
	v_cndmask_b32_e64 v95, 0, v179, s[38:39]
	v_cndmask_b32_e64 v96, 0, v178, s[38:39]
	s_nop 0
	v_lshlrev_b32_e32 v26, 16, v94
	v_fmac_f32_e32 v22, v152, v26
	v_lshlrev_b32_e32 v26, 16, v98
	v_fmac_f32_e32 v18, v58, v26
	v_and_b32_e32 v26, 0xffff0000, v94
	v_fmac_f32_e32 v23, v153, v26
	v_and_b32_e32 v26, 0xffff0000, v98
	v_fmac_f32_e32 v19, v59, v26
	v_lshlrev_b32_e32 v26, 16, v93
	v_fmac_f32_e32 v24, v154, v26
	v_lshlrev_b32_e32 v26, 16, v97
	v_fmac_f32_e32 v20, v60, v26
	v_and_b32_e32 v26, 0xffff0000, v93
	v_fmac_f32_e32 v25, v155, v26
	v_and_b32_e32 v26, 0xffff0000, v97
	v_fmac_f32_e32 v237, v61, v26
	v_lshlrev_b32_e32 v26, 16, v92
	v_fmac_f32_e32 v14, v144, v26
	v_lshlrev_b32_e32 v26, 16, v96
	v_fmac_f32_e32 v10, v50, v26
	v_and_b32_e32 v26, 0xffff0000, v92
	v_fmac_f32_e32 v15, v145, v26
	v_and_b32_e32 v26, 0xffff0000, v96
	v_fmac_f32_e32 v11, v51, v26
	v_lshlrev_b32_e32 v26, 16, v91
	v_fmac_f32_e32 v16, v146, v26
	v_lshlrev_b32_e32 v26, 16, v95
	v_fmac_f32_e32 v12, v52, v26
	v_and_b32_e32 v26, 0xffff0000, v91
	v_fmac_f32_e32 v241, v147, v26
	v_and_b32_e32 v26, 0xffff0000, v95
	v_fmac_f32_e32 v233, v53, v26
	v_readlane_b32 s50, v253, 32
	v_readlane_b32 s51, v253, 33
	s_waitcnt vmcnt(1)
	v_cndmask_b32_e64 v74, 0, v182, s[40:41]
	v_lshlrev_b32_e32 v26, 16, v74
	v_fmac_f32_e32 v22, v62, v26
	v_cndmask_b32_e64 v75, 0, v183, s[40:41]
	s_waitcnt vmcnt(0)
	v_cndmask_b32_e64 v78, 0, v204, s[40:41]
	v_lshlrev_b32_e32 v26, 16, v78
	v_fmac_f32_e32 v18, v70, v26
	v_and_b32_e32 v26, 0xffff0000, v74
	v_fmac_f32_e32 v23, v63, v26
	v_and_b32_e32 v26, 0xffff0000, v78
	v_cndmask_b32_e64 v79, 0, v205, s[40:41]
	v_fmac_f32_e32 v19, v71, v26
	v_lshlrev_b32_e32 v26, 16, v75
	v_fmac_f32_e32 v24, v64, v26
	v_lshlrev_b32_e32 v26, 16, v79
	v_fmac_f32_e32 v20, v72, v26
	v_and_b32_e32 v26, 0xffff0000, v75
	v_cndmask_b32_e64 v76, 0, v184, s[40:41]
	v_fmac_f32_e32 v25, v65, v26
	v_and_b32_e32 v26, 0xffff0000, v79
	v_cndmask_b32_e64 v80, 0, v206, s[40:41]
	v_fmac_f32_e32 v237, v73, v26
	v_lshlrev_b32_e32 v26, 16, v76
	v_fmac_f32_e32 v14, v54, v26
	v_lshlrev_b32_e32 v26, 16, v80
	v_fmac_f32_e32 v10, v66, v26
	v_and_b32_e32 v26, 0xffff0000, v76
	v_cndmask_b32_e64 v77, 0, v185, s[40:41]
	v_fmac_f32_e32 v15, v55, v26
	v_and_b32_e32 v26, 0xffff0000, v80
	v_cndmask_b32_e64 v81, 0, v207, s[40:41]
	v_fmac_f32_e32 v11, v67, v26
	v_lshlrev_b32_e32 v26, 16, v77
	v_fmac_f32_e32 v16, v56, v26
	v_lshlrev_b32_e32 v26, 16, v81
	v_fmac_f32_e32 v12, v68, v26
	v_and_b32_e32 v26, 0xffff0000, v77
	v_fmac_f32_e32 v241, v57, v26
	v_and_b32_e32 v26, 0xffff0000, v81
	v_fmac_f32_e32 v233, v69, v26
	v_bfe_u32 v26, v18, 16, 1
	v_add3_u32 v18, v18, v26, s94
	ds_write_b16_d16_hi v82, v18 offset:12800
	v_bfe_u32 v18, v22, 16, 1
	v_add3_u32 v18, v22, v18, s94
	ds_write_b16_d16_hi v82, v18 offset:28672
	v_bfe_u32 v18, v19, 16, 1
	v_add3_u32 v18, v19, v18, s94
	ds_write_b16_d16_hi v82, v18 offset:14336
	v_bfe_u32 v18, v23, 16, 1
	v_add3_u32 v18, v23, v18, s94
	ds_write_b16_d16_hi v82, v18 offset:29184
	v_bfe_u32 v18, v20, 16, 1
	v_add3_u32 v18, v20, v18, s94
	ds_write_b16_d16_hi v82, v18 offset:15872
	v_bfe_u32 v18, v24, 16, 1
	v_add3_u32 v18, v24, v18, s94
	ds_write_b16_d16_hi v82, v18 offset:29696
	v_bfe_u32 v18, v237, 16, 1
	v_add3_u32 v18, v237, v18, s94
	ds_write_b16_d16_hi v82, v18 offset:17408
	v_bfe_u32 v18, v25, 16, 1
	v_add3_u32 v18, v25, v18, s94
	ds_write_b16_d16_hi v82, v18 offset:30208
	v_bfe_u32 v18, v10, 16, 1
	v_add3_u32 v10, v10, v18, s94
	ds_write_b16_d16_hi v82, v10 offset:18944
	v_bfe_u32 v10, v14, 16, 1
	v_add3_u32 v10, v14, v10, s94
	ds_write_b16_d16_hi v82, v10 offset:30720
	v_bfe_u32 v10, v11, 16, 1
	v_add3_u32 v10, v11, v10, s94
	ds_write_b16_d16_hi v82, v10 offset:20480
	v_bfe_u32 v10, v15, 16, 1
	v_add3_u32 v10, v15, v10, s94
	ds_write_b16_d16_hi v82, v10 offset:31232
	v_bfe_u32 v10, v12, 16, 1
	v_add3_u32 v10, v12, v10, s94
	ds_write_b16_d16_hi v82, v10 offset:22016
	v_bfe_u32 v10, v16, 16, 1
	v_add3_u32 v10, v16, v10, s94
	ds_write_b16_d16_hi v82, v10 offset:31744
	v_bfe_u32 v10, v233, 16, 1
	v_add3_u32 v10, v233, v10, s94
	ds_write_b16_d16_hi v82, v10 offset:23552
	v_bfe_u32 v10, v241, 16, 1
	v_add3_u32 v10, v241, v10, s94
	ds_write_b16_d16_hi v82, v10 offset:32256
	v_mbcnt_hi_u32_b32 v10, -1, v194
	v_and_b32_e32 v11, 64, v10
	v_add_u32_e32 v11, 64, v11
	v_xor_b32_e32 v12, 32, v10
	v_cmp_lt_i32_e32 vcc, v12, v11
	v_lshl_add_u64 v[22:23], s[50:51], 0, v[160:161]
	s_movk_i32 s50, 0x600
	v_cndmask_b32_e32 v12, v10, v12, vcc
	v_lshlrev_b32_e32 v29, 2, v12
	v_xor_b32_e32 v12, 16, v10
	v_cmp_lt_i32_e32 vcc, v12, v11
	v_add_u32_e32 v25, s17, v126
	v_add_u32_e32 v28, v25, v160
	v_cndmask_b32_e32 v12, v10, v12, vcc
	v_lshlrev_b32_e32 v30, 2, v12
	v_xor_b32_e32 v12, 8, v10
	v_cmp_lt_i32_e32 vcc, v12, v11
	s_waitcnt lgkmcnt(0)
	v_mov_b32_e32 v13, v233
	v_mov_b32_e32 v17, v241
	v_mov_b32_e32 v21, v237
	v_mov_b32_e32 v34, v242
	v_mov_b32_e32 v35, v243
	v_mov_b32_e32 v36, v244
	v_mov_b32_e32 v37, v245
	v_mov_b32_e32 v42, v144
	v_mov_b32_e32 v43, v145
	v_mov_b32_e32 v44, v146
	v_mov_b32_e32 v45, v147
	v_mov_b32_e32 v46, v152
	v_mov_b32_e32 v47, v153
	v_mov_b32_e32 v48, v154
	v_mov_b32_e32 v49, v155
	s_barrier
	v_cndmask_b32_e32 v12, v10, v12, vcc
	v_lshlrev_b32_e32 v31, 2, v12
	v_xor_b32_e32 v12, 4, v10
	v_cmp_lt_i32_e32 vcc, v12, v11
	s_nop 1
	v_cndmask_b32_e32 v12, v10, v12, vcc
	v_lshlrev_b32_e32 v32, 2, v12
	v_xor_b32_e32 v12, 2, v10
	v_cmp_lt_i32_e32 vcc, v12, v11
	s_nop 1
	v_cndmask_b32_e32 v12, v10, v12, vcc
	v_lshlrev_b32_e32 v33, 2, v12
	v_xor_b32_e32 v12, 1, v10
	v_cmp_lt_i32_e32 vcc, v12, v11
	s_nop 1
	v_cndmask_b32_e32 v10, v10, v12, vcc
	v_lshlrev_b32_e32 v34, 2, v10
	v_lshlrev_b32_e32 v10, 3, v130
	v_sub_u32_e32 v35, v10, v129
	v_lshlrev_b32_e32 v10, 4, v129
	v_lshlrev_b32_e32 v11, 1, v35
	v_lshl_or_b32 v37, v130, 2, v10
	v_mul_lo_u32 v10, v1, s50
	v_and_b32_e32 v36, 2, v11
	v_lshl_or_b32 v10, v129, 5, v10
	v_and_b32_e32 v11, 48, v125
	v_lshl_add_u32 v38, v37, 1, s17
	v_add3_u32 v41, v10, v11, s17

.LBB0_749:
	s_or_b64 exec, exec, s[42:43]
	v_add_u32_e32 v0, s21, v0
	v_mov_b64_e32 v[2:3], s[6:7]
	v_ashrrev_i32_e32 v1, 31, v0
	v_mad_i64_i32 v[2:3], s[22:23], v0, s0, v[2:3]
	s_mov_b64 s[22:23], 0x3000
	v_lshlrev_b64 v[0:1], 12, v[0:1]
	v_lshl_add_u64 v[22:23], v[2:3], 0, s[22:23]
	v_lshl_add_u64 v[0:1], s[30:31], 0, v[0:1]
	s_mov_b64 s[22:23], 0xcc00c00
	v_lshl_add_u64 v[20:21], v[0:1], 0, s[22:23]
	s_mov_b64 s[22:23], 0x2800
	v_lshl_add_u64 v[28:29], v[104:105], 0, s[22:23]
	v_lshl_add_u64 v[0:1], v[28:29], 0, s[70:71]
	s_waitcnt lgkmcnt(0)
	s_barrier
	global_load_dwordx4 v[0:3], v[0:1], off
	v_lshl_add_u64 v[26:27], v[106:107], 0, s[22:23]
	v_lshl_add_u64 v[24:25], v[108:109], 0, s[22:23]
	s_add_u32 s44, s46, 0x2000
	s_addc_u32 s45, s47, 0
	s_add_u32 s42, s46, 0x3800
	s_addc_u32 s43, s47, 0
	v_lshl_add_u64 v[30:31], v[20:21], 0, s[70:71]
	s_waitcnt vmcnt(1)
	v_lshl_add_u64 v[204:205], v[26:27], 0, s[70:71]
	global_load_dwordx4 v[206:209], v[204:205], off
	v_lshl_add_u64 v[210:211], v[24:25], 0, s[70:71]
	global_load_dwordx4 v[212:215], v[210:211], off
	v_lshl_add_u64 v[216:217], v[22:23], 0, s[70:71]
	global_load_dwordx4 v[218:221], v[216:217], off
	global_load_dwordx4 v[222:225], v161, s[48:49] offset:2064
	global_load_dwordx4 v[48:51], v161, s[48:49] offset:2048
	global_load_dwordx4 v[226:229], v161, s[46:47] offset:2064
	global_load_dwordx4 v[52:55], v161, s[46:47] offset:2048
	global_load_dwordx4 v[230:233], v161, s[44:45] offset:16
	global_load_dwordx4 v[56:59], v196, s[46:47]
	global_load_dwordx4 v[234:237], v161, s[42:43] offset:16
	global_load_dwordx4 v[238:241], v197, s[46:47] offset:2048
	s_lshl_b32 s70, s20, 1
	v_lshl_add_u64 v[66:67], v[28:29], 0, s[70:71]
	global_load_dwordx4 v[68:71], v[66:67], off
	v_lshl_add_u64 v[204:205], v[26:27], 0, s[70:71]
	global_load_dwordx4 v[72:75], v[204:205], off
	v_lshl_add_u64 v[210:211], v[24:25], 0, s[70:71]
	global_load_dwordx4 v[76:79], v[210:211], off
	v_lshl_add_u64 v[216:217], v[22:23], 0, s[70:71]
	global_load_dwordx4 v[84:87], v[216:217], off
	global_load_dwordx4 v[88:91], v161, s[48:49] offset:2096
	global_load_dwordx4 v[110:113], v161, s[48:49] offset:2080
	global_load_dwordx4 v[114:117], v161, s[46:47] offset:2096
	global_load_dwordx4 v[22:25], v161, s[46:47] offset:2080
	global_load_dwordx4 v[26:29], v196, s[46:47] offset:32
	global_load_dwordx4 v[118:121], v197, s[46:47] offset:2080
	s_nop 0
	s_nop 0
	s_nop 0
	s_nop 0
	s_nop 0
	s_nop 0
	s_nop 0
	s_nop 0
	s_nop 0
	s_nop 0
	s_nop 0
	s_nop 0
	s_nop 0
	s_nop 0
	s_waitcnt vmcnt(21)
	v_cndmask_b32_e64 v6, 0, v1, s[36:37]
	v_cndmask_b32_e64 v7, 0, v0, s[36:37]
	s_nop 0
	v_cndmask_b32_e64 v4, 0, v3, s[36:37]
	v_cndmask_b32_e64 v5, 0, v2, s[36:37]
	s_nop 0
	v_and_b32_e32 v13, 0xffff0000, v7
	v_lshlrev_b32_e32 v12, 16, v7
	v_and_b32_e32 v43, 0xffff0000, v6
	v_lshlrev_b32_e32 v42, 16, v6
	v_and_b32_e32 v39, 0xffff0000, v5
	v_lshlrev_b32_e32 v38, 16, v5
	v_and_b32_e32 v35, 0xffff0000, v4
	v_lshlrev_b32_e32 v34, 16, v4
	s_waitcnt vmcnt(20)
	v_cndmask_b32_e64 v10, 0, v207, s[38:39]
	v_cndmask_b32_e64 v11, 0, v206, s[38:39]
	s_nop 0
	v_cndmask_b32_e64 v8, 0, v209, s[38:39]
	v_cndmask_b32_e64 v9, 0, v208, s[38:39]
	s_nop 0
	v_and_b32_e32 v17, 0xffff0000, v11
	v_lshlrev_b32_e32 v16, 16, v11
	v_and_b32_e32 v45, 0xffff0000, v10
	v_lshlrev_b32_e32 v44, 16, v10
	v_and_b32_e32 v41, 0xffff0000, v9
	v_lshlrev_b32_e32 v40, 16, v9
	v_and_b32_e32 v37, 0xffff0000, v8
	v_lshlrev_b32_e32 v36, 16, v8
	s_waitcnt vmcnt(19)
	v_cndmask_b32_e64 v64, 0, v213, s[40:41]
	v_cndmask_b32_e64 v60, 0, v212, s[40:41]
	s_nop 0
	v_cndmask_b32_e64 v46, 0, v215, s[40:41]
	v_cndmask_b32_e64 v47, 0, v214, s[40:41]
	s_nop 0
	s_nop 0
	s_nop 0
	s_nop 0
	s_nop 0
	s_nop 0
	s_nop 0
	s_waitcnt vmcnt(15)
	v_pk_fma_f32 v[4:5], v[226:227], v[38:39], v[222:223]
	s_waitcnt vmcnt(14)
	v_pk_fma_f32 v[18:19], v[52:53], v[12:13], v[48:49]
	s_nop 0
	s_nop 0
	v_and_b32_e32 v49, 0xffff0000, v60
	v_lshlrev_b32_e32 v48, 16, v60
	v_pk_fma_f32 v[42:43], v[54:55], v[42:43], v[50:51]
	v_and_b32_e32 v9, 0xffff0000, v47
	v_lshlrev_b32_e32 v8, 16, v47
	v_pk_fma_f32 v[6:7], v[228:229], v[34:35], v[224:225]
	s_waitcnt vmcnt(13)
	v_pk_fma_f32 v[4:5], v[230:231], v[40:41], v[4:5]
	s_waitcnt vmcnt(12)
	v_pk_fma_f32 v[32:33], v[56:57], v[16:17], v[18:19]
	s_nop 0
	s_nop 0
	v_and_b32_e32 v56, 0xffff0000, v218
	v_lshlrev_b32_e32 v0, 16, v218
	v_pk_fma_f32 v[42:43], v[58:59], v[44:45], v[42:43]
	v_and_b32_e32 v45, 0xffff0000, v64
	v_lshlrev_b32_e32 v44, 16, v64
	v_pk_fma_f32 v[6:7], v[232:233], v[36:37], v[6:7]
	s_waitcnt vmcnt(11)
	v_pk_fma_f32 v[4:5], v[234:235], v[8:9], v[4:5]
	s_waitcnt vmcnt(10)
	v_pk_fma_f32 v[32:33], v[238:239], v[48:49], v[32:33]
	ds_read_u16 v49, v82 offset:512
	ds_read_u16 v52, v82 offset:2048
	v_mul_f32_e32 v48, 0xbfb8aa3b, v0
	v_exp_f32_e32 v48, v48
	v_pk_fma_f32 v[42:43], v[240:241], v[44:45], v[42:43]
	v_and_b32_e32 v16, 0xffff0000, v220
	s_waitcnt lgkmcnt(0)
	v_lshlrev_b32_e32 v53, 16, v52
	v_lshlrev_b32_e32 v52, 16, v49
	v_mul_f32_e32 v49, 0xbfb8aa3b, v56
	v_exp_f32_e32 v49, v49
	v_pk_mul_f32 v[32:33], v[32:33], v[52:53]
	v_lshlrev_b32_e32 v2, 16, v220
	v_mul_f32_e32 v8, 0xbfb8aa3b, v2
	v_pk_add_f32 v[48:49], v[48:49], 1.0 op_sel_hi:[1,0]
	v_exp_f32_e32 v8, v8
	v_div_scale_f32 v52, s[22:23], v49, v49, v56
	v_rcp_f32_e32 v53, v52
	s_nop 0
	v_fma_f32 v57, -v52, v53, 1.0
	v_fmac_f32_e32 v53, v57, v53
	v_div_scale_f32 v57, vcc, v56, v49, v56
	v_mul_f32_e32 v60, v57, v53
	v_fma_f32 v61, -v52, v60, v57
	v_fmac_f32_e32 v60, v61, v53
	v_fma_f32 v52, -v52, v60, v57
	v_div_fmas_f32 v52, v52, v53, v60
	v_div_fixup_f32 v49, v52, v49, v56
	v_div_scale_f32 v52, s[22:23], v48, v48, v0
	v_rcp_f32_e32 v53, v52
	s_nop 0
	v_fma_f32 v56, -v52, v53, 1.0
	v_fmac_f32_e32 v53, v56, v53
	v_div_scale_f32 v56, vcc, v0, v48, v0
	v_mul_f32_e32 v57, v56, v53
	v_fma_f32 v60, -v52, v57, v56
	v_fmac_f32_e32 v57, v60, v53
	v_fma_f32 v52, -v52, v57, v56
	v_div_fmas_f32 v52, v52, v53, v57
	v_div_fixup_f32 v48, v52, v48, v0
	v_pk_mul_f32 v[32:33], v[48:49], v[32:33]
	v_and_b32_e32 v48, 0xffff0000, v219
	v_lshlrev_b32_e32 v49, 16, v219
	ds_read_u16 v1, v82 offset:3584
	ds_read_u16 v44, v82 offset:5120
	v_mul_f32_e32 v0, 0xbfb8aa3b, v49
	v_exp_f32_e32 v0, v0
	ds_read_u16 v9, v82 offset:6656
	ds_read_u16 v12, v82 offset:8192
	s_waitcnt lgkmcnt(2)
	v_lshlrev_b32_e32 v45, 16, v44
	v_lshlrev_b32_e32 v44, 16, v1
	v_mul_f32_e32 v1, 0xbfb8aa3b, v48
	v_exp_f32_e32 v1, v1
	v_pk_mul_f32 v[42:43], v[42:43], v[44:45]
	s_waitcnt lgkmcnt(0)
	v_lshlrev_b32_e32 v13, 16, v12
	v_lshlrev_b32_e32 v12, 16, v9
	v_pk_add_f32 v[0:1], v[0:1], 1.0 op_sel_hi:[1,0]
	v_mul_f32_e32 v9, 0xbfb8aa3b, v16
	v_div_scale_f32 v44, s[22:23], v1, v1, v48
	v_rcp_f32_e32 v45, v44
	v_exp_f32_e32 v9, v9
	v_pk_mul_f32 v[4:5], v[4:5], v[12:13]
	v_fma_f32 v50, -v44, v45, 1.0
	v_fmac_f32_e32 v45, v50, v45
	v_div_scale_f32 v50, vcc, v48, v1, v48
	v_mul_f32_e32 v51, v50, v45
	v_fma_f32 v52, -v44, v51, v50
	v_fmac_f32_e32 v51, v52, v45
	v_fma_f32 v44, -v44, v51, v50
	v_div_fmas_f32 v44, v44, v45, v51
	v_div_fixup_f32 v1, v44, v1, v48
	v_div_scale_f32 v44, s[22:23], v0, v0, v49
	v_rcp_f32_e32 v45, v44
	v_pk_add_f32 v[8:9], v[8:9], 1.0 op_sel_hi:[1,0]
	v_fma_f32 v48, -v44, v45, 1.0
	v_div_scale_f32 v12, s[22:23], v9, v9, v16
	v_fmac_f32_e32 v45, v48, v45
	v_div_scale_f32 v48, vcc, v49, v0, v49
	v_rcp_f32_e32 v13, v12
	v_mul_f32_e32 v50, v48, v45
	v_fma_f32 v51, -v44, v50, v48
	v_fmac_f32_e32 v50, v51, v45
	v_fma_f32 v44, -v44, v50, v48
	v_fma_f32 v17, -v12, v13, 1.0
	v_div_fmas_f32 v44, v44, v45, v50
	v_fmac_f32_e32 v13, v17, v13
	v_div_scale_f32 v17, vcc, v16, v9, v16
	v_mul_f32_e32 v38, v17, v13
	v_fma_f32 v39, -v12, v38, v17
	v_fmac_f32_e32 v38, v39, v13
	v_fma_f32 v12, -v12, v38, v17
	v_div_fmas_f32 v12, v12, v13, v38
	v_div_fixup_f32 v9, v12, v9, v16
	v_div_scale_f32 v12, s[22:23], v8, v8, v2
	v_rcp_f32_e32 v13, v12
	v_div_fixup_f32 v0, v44, v0, v49
	v_pk_mul_f32 v[0:1], v[0:1], v[42:43]
	v_fma_f32 v16, -v12, v13, 1.0
	v_fmac_f32_e32 v13, v16, v13
	v_div_scale_f32 v16, vcc, v2, v8, v2
	v_mul_f32_e32 v17, v16, v13
	v_fma_f32 v38, -v12, v17, v16
	v_fmac_f32_e32 v17, v38, v13
	v_fma_f32 v12, -v12, v17, v16
	v_div_fmas_f32 v12, v12, v13, v17
	v_div_fixup_f32 v8, v12, v8, v2
	v_pk_mul_f32 v[4:5], v[8:9], v[4:5]
	v_and_b32_e32 v9, 0xffff0000, v46
	v_lshlrev_b32_e32 v8, 16, v46
	v_pk_fma_f32 v[6:7], v[236:237], v[8:9], v[6:7]
	v_and_b32_e32 v9, 0xffff0000, v221
	v_lshlrev_b32_e32 v8, 16, v221
	ds_read_u16 v3, v82 offset:9728
	ds_read_u16 v10, v82 offset:11264
	v_mul_f32_e32 v2, 0xbfb8aa3b, v8
	v_exp_f32_e32 v2, v2
	s_waitcnt lgkmcnt(0)
	v_lshlrev_b32_e32 v11, 16, v10
	v_lshlrev_b32_e32 v10, 16, v3
	v_mul_f32_e32 v3, 0xbfb8aa3b, v9
	v_exp_f32_e32 v3, v3
	v_pk_mul_f32 v[6:7], v[6:7], v[10:11]
	v_pk_add_f32 v[2:3], v[2:3], 1.0 op_sel_hi:[1,0]
	s_nop 0
	v_div_scale_f32 v10, s[22:23], v3, v3, v9
	v_rcp_f32_e32 v11, v10
	s_nop 0
	v_fma_f32 v12, -v10, v11, 1.0
	v_fmac_f32_e32 v11, v12, v11
	v_div_scale_f32 v12, vcc, v9, v3, v9
	v_mul_f32_e32 v13, v12, v11
	v_fma_f32 v14, -v10, v13, v12
	v_fmac_f32_e32 v13, v14, v11
	v_fma_f32 v10, -v10, v13, v12
	v_div_fmas_f32 v10, v10, v11, v13
	v_div_fixup_f32 v3, v10, v3, v9
	v_div_scale_f32 v9, s[22:23], v2, v2, v8
	v_rcp_f32_e32 v10, v9
	s_nop 0
	v_fma_f32 v11, -v9, v10, 1.0
	v_fmac_f32_e32 v10, v11, v10
	v_div_scale_f32 v11, vcc, v8, v2, v8
	v_mul_f32_e32 v12, v11, v10
	v_fma_f32 v13, -v9, v12, v11
	v_fmac_f32_e32 v12, v13, v10
	v_fma_f32 v9, -v9, v12, v11
	v_div_fmas_f32 v9, v9, v10, v12
	v_div_fixup_f32 v2, v9, v2, v8
	v_pk_mul_f32 v[2:3], v[2:3], v[6:7]
	v_bfe_u32 v12, v33, 16, 1
	v_bfe_u32 v13, v32, 16, 1
	v_add3_u32 v13, v32, v13, s94
	v_add3_u32 v12, v33, v12, s94
	v_cvt_pk_bf16_f32 v0, v0, v1
	v_cvt_pk_bf16_f32 v4, v4, v5
	v_cvt_pk_bf16_f32 v2, v2, v3
	v_mov_b32_e32 v3, v2
	v_mov_b32_e32 v2, v4
	v_mov_b32_e32 v1, v0
	v_perm_b32 v0, v12, v13, s95
	global_store_dwordx4 v[30:31], v[0:3], off
	v_mov_b32_e32 v15, v233
	v_mov_b32_e32 v18, v236
	v_mov_b32_e32 v19, v237
	v_mov_b32_e32 v62, v240
	v_mov_b32_e32 v63, v241
	v_lshl_add_u64 v[30:31], v[20:21], 0, s[70:71]
	s_nop 0
	s_nop 0
	s_nop 0
	s_nop 0
	s_nop 0
	s_nop 0
	s_nop 0
	s_nop 0
	s_nop 0
	s_nop 0
	s_nop 0
	s_nop 0
	s_nop 0
	s_nop 0
	s_nop 0
	s_waitcnt vmcnt(10)
	v_cndmask_b32_e64 v6, 0, v69, s[36:37]
	v_cndmask_b32_e64 v7, 0, v68, s[36:37]
	s_nop 0
	v_cndmask_b32_e64 v4, 0, v71, s[36:37]
	v_cndmask_b32_e64 v5, 0, v70, s[36:37]
	s_nop 0
	v_and_b32_e32 v13, 0xffff0000, v7
	v_lshlrev_b32_e32 v12, 16, v7
	v_and_b32_e32 v41, 0xffff0000, v6
	v_lshlrev_b32_e32 v40, 16, v6
	v_and_b32_e32 v37, 0xffff0000, v5
	v_lshlrev_b32_e32 v36, 16, v5
	v_and_b32_e32 v33, 0xffff0000, v4
	v_lshlrev_b32_e32 v32, 16, v4
	s_waitcnt vmcnt(9)
	v_cndmask_b32_e64 v10, 0, v73, s[38:39]
	v_cndmask_b32_e64 v11, 0, v72, s[38:39]
	s_nop 0
	v_cndmask_b32_e64 v8, 0, v75, s[38:39]
	v_cndmask_b32_e64 v9, 0, v74, s[38:39]
	s_nop 0
	v_and_b32_e32 v17, 0xffff0000, v11
	v_lshlrev_b32_e32 v16, 16, v11
	v_and_b32_e32 v43, 0xffff0000, v10
	v_lshlrev_b32_e32 v42, 16, v10
	v_and_b32_e32 v39, 0xffff0000, v9
	v_lshlrev_b32_e32 v38, 16, v9
	v_and_b32_e32 v35, 0xffff0000, v8
	v_lshlrev_b32_e32 v34, 16, v8
	s_add_u32 s38, s46, 0x2020
	s_addc_u32 s39, s47, 0
	s_add_u32 s36, s46, 0x3820
	s_addc_u32 s37, s47, 0
	s_waitcnt vmcnt(8)
	v_cndmask_b32_e64 v46, 0, v77, s[40:41]
	v_cndmask_b32_e64 v47, 0, v76, s[40:41]
	s_nop 0
	v_cndmask_b32_e64 v44, 0, v79, s[40:41]
	v_cndmask_b32_e64 v45, 0, v78, s[40:41]
	s_nop 0
	s_nop 0
	s_nop 0
	s_nop 0
	s_nop 0
	s_nop 0
	s_waitcnt vmcnt(4)
	v_pk_fma_f32 v[4:5], v[114:115], v[36:37], v[88:89]
	s_waitcnt vmcnt(3)
	v_pk_fma_f32 v[18:19], v[22:23], v[12:13], v[110:111]
	global_load_dwordx4 v[12:15], v161, s[38:39] offset:16
	s_nop 0
	v_pk_fma_f32 v[20:21], v[24:25], v[40:41], v[112:113]
	v_and_b32_e32 v25, 0xffff0000, v46
	v_lshlrev_b32_e32 v24, 16, v46
	v_and_b32_e32 v9, 0xffff0000, v45
	v_lshlrev_b32_e32 v8, 16, v45
	v_pk_fma_f32 v[6:7], v[116:117], v[32:33], v[90:91]
	s_waitcnt vmcnt(0)
	v_pk_fma_f32 v[4:5], v[12:13], v[38:39], v[4:5]
	v_pk_fma_f32 v[22:23], v[26:27], v[16:17], v[18:19]
	global_load_dwordx4 v[16:19], v161, s[36:37] offset:16
	s_nop 0
	v_and_b32_e32 v27, 0xffff0000, v47
	v_lshlrev_b32_e32 v26, 16, v47
	v_and_b32_e32 v47, 0xffff0000, v84
	v_lshlrev_b32_e32 v0, 16, v84
	v_pk_fma_f32 v[20:21], v[28:29], v[42:43], v[20:21]
	v_pk_fma_f32 v[6:7], v[14:15], v[34:35], v[6:7]
	s_waitcnt vmcnt(0)
	v_pk_fma_f32 v[4:5], v[16:17], v[8:9], v[4:5]
	v_pk_fma_f32 v[22:23], v[118:119], v[26:27], v[22:23]
	ds_read_u16 v27, v82 offset:12800
	ds_read_u16 v48, v82 offset:14336
	v_mul_f32_e32 v26, 0xbfb8aa3b, v0
	v_exp_f32_e32 v26, v26
	v_pk_fma_f32 v[20:21], v[120:121], v[24:25], v[20:21]
	v_and_b32_e32 v16, 0xffff0000, v86
	s_waitcnt lgkmcnt(0)
	v_lshlrev_b32_e32 v49, 16, v48
	v_lshlrev_b32_e32 v48, 16, v27
	v_mul_f32_e32 v27, 0xbfb8aa3b, v47
	v_exp_f32_e32 v27, v27
	v_pk_mul_f32 v[22:23], v[22:23], v[48:49]
	v_lshlrev_b32_e32 v2, 16, v86
	v_mul_f32_e32 v8, 0xbfb8aa3b, v2
	v_pk_add_f32 v[26:27], v[26:27], 1.0 op_sel_hi:[1,0]
	v_exp_f32_e32 v8, v8
	v_div_scale_f32 v48, s[20:21], v27, v27, v47
	v_rcp_f32_e32 v49, v48
	s_nop 0
	v_fma_f32 v52, -v48, v49, 1.0
	v_fmac_f32_e32 v49, v52, v49
	v_div_scale_f32 v52, vcc, v47, v27, v47
	v_mul_f32_e32 v53, v52, v49
	v_fma_f32 v54, -v48, v53, v52
	v_fmac_f32_e32 v53, v54, v49
	v_fma_f32 v48, -v48, v53, v52
	v_div_fmas_f32 v48, v48, v49, v53
	v_div_fixup_f32 v27, v48, v27, v47
	v_div_scale_f32 v47, s[20:21], v26, v26, v0
	v_rcp_f32_e32 v48, v47
	s_nop 0
	v_fma_f32 v49, -v47, v48, 1.0
	v_fmac_f32_e32 v48, v49, v48
	v_div_scale_f32 v49, vcc, v0, v26, v0
	v_mul_f32_e32 v52, v49, v48
	v_fma_f32 v53, -v47, v52, v49
	v_fmac_f32_e32 v52, v53, v48
	v_fma_f32 v47, -v47, v52, v49
	v_div_fmas_f32 v47, v47, v48, v52
	v_div_fixup_f32 v26, v47, v26, v0
	v_pk_mul_f32 v[22:23], v[26:27], v[22:23]
	v_and_b32_e32 v26, 0xffff0000, v85
	v_lshlrev_b32_e32 v27, 16, v85
	ds_read_u16 v1, v82 offset:15872
	ds_read_u16 v24, v82 offset:17408
	v_mul_f32_e32 v0, 0xbfb8aa3b, v27
	v_exp_f32_e32 v0, v0
	ds_read_u16 v9, v82 offset:18944
	ds_read_u16 v12, v82 offset:20480
	s_waitcnt lgkmcnt(2)
	v_lshlrev_b32_e32 v25, 16, v24
	v_lshlrev_b32_e32 v24, 16, v1
	v_mul_f32_e32 v1, 0xbfb8aa3b, v26
	v_exp_f32_e32 v1, v1
	v_pk_mul_f32 v[20:21], v[20:21], v[24:25]
	s_waitcnt lgkmcnt(0)
	v_lshlrev_b32_e32 v13, 16, v12
	v_lshlrev_b32_e32 v12, 16, v9
	v_pk_add_f32 v[0:1], v[0:1], 1.0 op_sel_hi:[1,0]
	v_mul_f32_e32 v9, 0xbfb8aa3b, v16
	v_div_scale_f32 v24, s[20:21], v1, v1, v26
	v_rcp_f32_e32 v25, v24
	v_exp_f32_e32 v9, v9
	v_pk_mul_f32 v[4:5], v[4:5], v[12:13]
	v_fma_f32 v28, -v24, v25, 1.0
	v_fmac_f32_e32 v25, v28, v25
	v_div_scale_f32 v28, vcc, v26, v1, v26
	v_mul_f32_e32 v29, v28, v25
	v_fma_f32 v40, -v24, v29, v28
	v_fmac_f32_e32 v29, v40, v25
	v_fma_f32 v24, -v24, v29, v28
	v_div_fmas_f32 v24, v24, v25, v29
	v_div_fixup_f32 v1, v24, v1, v26
	v_div_scale_f32 v24, s[20:21], v0, v0, v27
	v_rcp_f32_e32 v25, v24
	v_pk_add_f32 v[8:9], v[8:9], 1.0 op_sel_hi:[1,0]
	v_fma_f32 v26, -v24, v25, 1.0
	v_fmac_f32_e32 v25, v26, v25
	v_div_scale_f32 v26, vcc, v27, v0, v27
	v_div_scale_f32 v12, s[20:21], v9, v9, v16
	v_mul_f32_e32 v28, v26, v25
	v_rcp_f32_e32 v13, v12
	v_fma_f32 v29, -v24, v28, v26
	v_fmac_f32_e32 v28, v29, v25
	v_fma_f32 v24, -v24, v28, v26
	v_div_fmas_f32 v24, v24, v25, v28
	v_fma_f32 v17, -v12, v13, 1.0
	v_div_fixup_f32 v0, v24, v0, v27
	v_fmac_f32_e32 v13, v17, v13
	v_div_scale_f32 v17, vcc, v16, v9, v16
	v_pk_mul_f32 v[0:1], v[0:1], v[20:21]
	v_mul_f32_e32 v20, v17, v13
	v_fma_f32 v21, -v12, v20, v17
	v_fmac_f32_e32 v20, v21, v13
	v_fma_f32 v12, -v12, v20, v17
	v_div_fmas_f32 v12, v12, v13, v20
	v_div_fixup_f32 v9, v12, v9, v16
	v_div_scale_f32 v12, s[20:21], v8, v8, v2
	v_rcp_f32_e32 v13, v12
	s_nop 0
	v_fma_f32 v16, -v12, v13, 1.0
	v_fmac_f32_e32 v13, v16, v13
	v_div_scale_f32 v16, vcc, v2, v8, v2
	v_mul_f32_e32 v17, v16, v13
	v_fma_f32 v20, -v12, v17, v16
	v_fmac_f32_e32 v17, v20, v13
	v_fma_f32 v12, -v12, v17, v16
	v_div_fmas_f32 v12, v12, v13, v17
	v_div_fixup_f32 v8, v12, v8, v2
	v_pk_mul_f32 v[4:5], v[8:9], v[4:5]
	v_and_b32_e32 v9, 0xffff0000, v44
	v_lshlrev_b32_e32 v8, 16, v44
	v_pk_fma_f32 v[6:7], v[18:19], v[8:9], v[6:7]
	v_and_b32_e32 v9, 0xffff0000, v87
	v_lshlrev_b32_e32 v8, 16, v87
	ds_read_u16 v3, v82 offset:22016
	ds_read_u16 v10, v82 offset:23552
	v_mul_f32_e32 v2, 0xbfb8aa3b, v8
	v_exp_f32_e32 v2, v2
	s_waitcnt lgkmcnt(0)
	v_lshlrev_b32_e32 v11, 16, v10
	v_lshlrev_b32_e32 v10, 16, v3
	v_mul_f32_e32 v3, 0xbfb8aa3b, v9
	v_exp_f32_e32 v3, v3
	v_pk_mul_f32 v[6:7], v[6:7], v[10:11]
	v_pk_add_f32 v[2:3], v[2:3], 1.0 op_sel_hi:[1,0]
	s_nop 0
	v_div_scale_f32 v10, s[20:21], v3, v3, v9
	v_rcp_f32_e32 v11, v10
	s_nop 0
	v_fma_f32 v12, -v10, v11, 1.0
	v_fmac_f32_e32 v11, v12, v11
	v_div_scale_f32 v12, vcc, v9, v3, v9
	v_mul_f32_e32 v13, v12, v11
	v_fma_f32 v14, -v10, v13, v12
	v_fmac_f32_e32 v13, v14, v11
	v_fma_f32 v10, -v10, v13, v12
	v_div_fmas_f32 v10, v10, v11, v13
	v_div_fixup_f32 v3, v10, v3, v9
	v_div_scale_f32 v9, s[20:21], v2, v2, v8
	v_rcp_f32_e32 v10, v9
	s_nop 0
	v_fma_f32 v11, -v9, v10, 1.0
	v_fmac_f32_e32 v10, v11, v10
	v_div_scale_f32 v11, vcc, v8, v2, v8
	v_mul_f32_e32 v12, v11, v10
	v_fma_f32 v13, -v9, v12, v11
	v_fmac_f32_e32 v12, v13, v10
	v_fma_f32 v9, -v9, v12, v11
	v_div_fmas_f32 v9, v9, v10, v12
	v_div_fixup_f32 v2, v9, v2, v8
	v_pk_mul_f32 v[2:3], v[2:3], v[6:7]
	v_bfe_u32 v12, v23, 16, 1
	v_bfe_u32 v13, v22, 16, 1
	v_add3_u32 v13, v22, v13, s94
	v_add3_u32 v12, v23, v12, s94
	v_cvt_pk_bf16_f32 v0, v0, v1
	v_cvt_pk_bf16_f32 v4, v4, v5
	v_cvt_pk_bf16_f32 v2, v2, v3
	v_mov_b32_e32 v3, v2
	v_mov_b32_e32 v2, v4
	v_mov_b32_e32 v1, v0
	v_perm_b32 v0, v12, v13, s95
	global_store_dwordx4 v[30:31], v[0:3], off
	v_mov_b32_e32 v50, v120
	v_mov_b32_e32 v51, v121
	v_mov_b32_e32 v206, v72
	v_mov_b32_e32 v207, v73
	v_mov_b32_e32 v208, v74
	v_mov_b32_e32 v209, v75
	v_mov_b32_e32 v212, v76
	v_mov_b32_e32 v213, v77
	v_mov_b32_e32 v214, v78
	v_mov_b32_e32 v215, v79
	v_mov_b32_e32 v218, v84
	v_mov_b32_e32 v219, v85
	v_mov_b32_e32 v220, v86
	v_mov_b32_e32 v221, v87
	v_mov_b32_e32 v222, v88
	v_mov_b32_e32 v223, v89
	v_mov_b32_e32 v224, v90
	v_mov_b32_e32 v225, v91
	v_mov_b32_e32 v226, v114
	v_mov_b32_e32 v227, v115
	v_mov_b32_e32 v228, v116
	v_mov_b32_e32 v229, v117
	s_barrier
